# speedup vs baseline: 1.0012x; 1.0012x over previous
; __device__ __forceinline__ void gemm_tile(const TileDesc& td, char* shm_c, const int wv) {
;     ...
;   } else if (mode == EPI_RESID) {
;     #pragma unroll
;     for (int ai = 0; ai < 2; ++ai)
;     #pragma unroll
;     for (int bj = 0; bj < 2; ++bj)
;     #pragma unroll
;     for (int m = 0; m < 4; ++m)
;     #pragma unroll
;     for (int n = 0; n < 2; ++n) {
;       long o = (long)(td.bcol + bj * 128 + n * 16 + br_l) * D + (td.brow + ai * 128 + m * 16 + ar_l);
;       float4 r = *(const float4*)(td.aux + o);
;       f32x4 v = acc[ai][bj][m][n];
;       r.x += v[0]; r.y += v[1]; r.z += v[2]; r.w += v[3];
;       *(float4*)(td.outf + o) = r;
;     }
.LBB0_498:
	v_mbcnt_lo_u32_b32 v128, -1, 0
	v_mbcnt_hi_u32_b32 v128, -1, v128
	s_sext_i32_i16 s27, s27
	v_lshrrev_b32_e32 v130, 2, v128
	v_and_or_b32 v128, v128, 15, s42
	v_and_or_b32 v132, v130, 12, s38
	v_lshl_or_b32 v140, s27, 8, v128
	v_ashrrev_i32_e32 v141, 31, v140
	v_lshl_add_u32 v132, s26, 8, v132
	v_lshlrev_b64 v[130:131], 12, v[140:141]
	v_ashrrev_i32_e32 v133, 31, v132
	v_lshl_add_u64 v[134:135], v[130:131], 0, v[132:133]
	v_lshlrev_b64 v[144:145], 2, v[134:135]
	v_lshl_add_u64 v[146:147], s[72:73], 0, v[144:145]
	v_lshl_add_u64 v[148:149], s[70:71], 0, v[144:145]
	v_add_co_u32_e32 v150, vcc, 0x40000, v146
	s_nop 1
	v_addc_co_u32_e32 v151, vcc, 0, v147, vcc
	v_add_co_u32_e32 v156, vcc, 0x40000, v148
	s_nop 1
	v_addc_co_u32_e32 v157, vcc, 0, v149, vcc
	v_add_co_u32_e32 v152, vcc, 0x200000, v146
	s_nop 1
	v_addc_co_u32_e32 v153, vcc, 0, v147, vcc
	v_add_co_u32_e32 v158, vcc, 0x200000, v148
	s_nop 1
	v_addc_co_u32_e32 v159, vcc, 0, v149, vcc
	v_add_co_u32_e32 v154, vcc, 0x240000, v146
	s_nop 1
	v_addc_co_u32_e32 v155, vcc, 0, v147, vcc
	v_add_co_u32_e32 v160, vcc, 0x240000, v148
	s_nop 1
	v_addc_co_u32_e32 v161, vcc, 0, v149, vcc
	s_add_i32 s59, s59, s91
	s_cmpk_lt_i32 s59, 0x400
	v_readlane_b32 s67, v255, 34
	global_load_dwordx4 v[164:167], v[146:147], off
	global_load_dwordx4 v[168:171], v[150:151], off
	global_load_dwordx4 v[172:175], v[146:147], off offset:64
	global_load_dwordx4 v[176:179], v[150:151], off offset:64
	global_load_dwordx4 v[180:183], v[146:147], off offset:128
	global_load_dwordx4 v[184:187], v[150:151], off offset:128
	global_load_dwordx4 v[188:191], v[146:147], off offset:192
	global_load_dwordx4 v[192:195], v[150:151], off offset:192
	global_load_dwordx4 v[196:199], v[152:153], off
	global_load_dwordx4 v[200:203], v[154:155], off
	global_load_dwordx4 v[204:207], v[152:153], off offset:64
	global_load_dwordx4 v[208:211], v[154:155], off offset:64
	global_load_dwordx4 v[212:215], v[152:153], off offset:128
	global_load_dwordx4 v[216:219], v[154:155], off offset:128
	global_load_dwordx4 v[220:223], v[152:153], off offset:192
	global_load_dwordx4 v[224:227], v[154:155], off offset:192
	s_waitcnt vmcnt(15)
	v_pk_add_f32 v[124:125], v[124:125], v[164:165]
	v_pk_add_f32 v[126:127], v[126:127], v[166:167]
	global_store_dwordx4 v[148:149], v[124:127], off
	global_load_dwordx4 v[164:167], v[146:147], off offset:512
	s_waitcnt vmcnt(16)
	v_pk_add_f32 v[120:121], v[120:121], v[168:169]
	v_pk_add_f32 v[122:123], v[122:123], v[170:171]
	global_store_dwordx4 v[156:157], v[120:123], off
	global_load_dwordx4 v[168:171], v[150:151], off offset:512
	s_waitcnt vmcnt(17)
	v_pk_add_f32 v[116:117], v[116:117], v[172:173]
	v_pk_add_f32 v[118:119], v[118:119], v[174:175]
	global_store_dwordx4 v[148:149], v[116:119], off offset:64
	global_load_dwordx4 v[172:175], v[146:147], off offset:576
	s_waitcnt vmcnt(18)
	v_pk_add_f32 v[112:113], v[112:113], v[176:177]
	v_pk_add_f32 v[114:115], v[114:115], v[178:179]
	global_store_dwordx4 v[156:157], v[112:115], off offset:64
	global_load_dwordx4 v[176:179], v[150:151], off offset:576
	s_waitcnt vmcnt(19)
	v_pk_add_f32 v[108:109], v[108:109], v[180:181]
	v_pk_add_f32 v[110:111], v[110:111], v[182:183]
	global_store_dwordx4 v[148:149], v[108:111], off offset:128
	global_load_dwordx4 v[180:183], v[146:147], off offset:640
	s_waitcnt vmcnt(20)
	v_pk_add_f32 v[104:105], v[104:105], v[184:185]
	v_pk_add_f32 v[106:107], v[106:107], v[186:187]
	global_store_dwordx4 v[156:157], v[104:107], off offset:128
	global_load_dwordx4 v[184:187], v[150:151], off offset:640
	s_waitcnt vmcnt(21)
	v_pk_add_f32 v[100:101], v[100:101], v[188:189]
	v_pk_add_f32 v[102:103], v[102:103], v[190:191]
	global_store_dwordx4 v[148:149], v[100:103], off offset:192
	global_load_dwordx4 v[188:191], v[146:147], off offset:704
	s_waitcnt vmcnt(22)
	v_pk_add_f32 v[96:97], v[96:97], v[192:193]
	v_pk_add_f32 v[98:99], v[98:99], v[194:195]
	global_store_dwordx4 v[156:157], v[96:99], off offset:192
	global_load_dwordx4 v[192:195], v[150:151], off offset:704
	s_waitcnt vmcnt(23)
	v_pk_add_f32 v[92:93], v[92:93], v[196:197]
	v_pk_add_f32 v[94:95], v[94:95], v[198:199]
	global_store_dwordx4 v[158:159], v[92:95], off
	global_load_dwordx4 v[196:199], v[152:153], off offset:512
	s_waitcnt vmcnt(24)
; __device__ __forceinline__ void gemm_tile(const TileDesc& td, char* shm_c, const int wv) {
;     ...
;   } else if (mode == EPI_RESID) {
;     #pragma unroll
;     for (int ai = 0; ai < 2; ++ai)
;     #pragma unroll
;     for (int bj = 0; bj < 2; ++bj)
;     #pragma unroll
;     for (int m = 0; m < 4; ++m)
;     #pragma unroll
;     for (int n = 0; n < 2; ++n) {
;       long o = (long)(td.bcol + bj * 128 + n * 16 + br_l) * D + (td.brow + ai * 128 + m * 16 + ar_l);
;       float4 r = *(const float4*)(td.aux + o);
;       f32x4 v = acc[ai][bj][m][n];
;       r.x += v[0]; r.y += v[1]; r.z += v[2]; r.w += v[3];
;       *(float4*)(td.outf + o) = r;
;     }
	v_pk_add_f32 v[88:89], v[88:89], v[200:201]
	v_pk_add_f32 v[90:91], v[90:91], v[202:203]
	global_store_dwordx4 v[160:161], v[88:91], off
	global_load_dwordx4 v[200:203], v[154:155], off offset:512
	s_waitcnt vmcnt(25)
	v_pk_add_f32 v[84:85], v[84:85], v[204:205]
	v_pk_add_f32 v[86:87], v[86:87], v[206:207]
	global_store_dwordx4 v[158:159], v[84:87], off offset:64
	global_load_dwordx4 v[204:207], v[152:153], off offset:576
	s_waitcnt vmcnt(26)
	v_pk_add_f32 v[80:81], v[80:81], v[208:209]
	v_pk_add_f32 v[82:83], v[82:83], v[210:211]
	global_store_dwordx4 v[160:161], v[80:83], off offset:64
	global_load_dwordx4 v[208:211], v[154:155], off offset:576
	s_waitcnt vmcnt(27)
	v_pk_add_f32 v[76:77], v[76:77], v[212:213]
	v_pk_add_f32 v[78:79], v[78:79], v[214:215]
	global_store_dwordx4 v[158:159], v[76:79], off offset:128
	global_load_dwordx4 v[212:215], v[152:153], off offset:640
	s_waitcnt vmcnt(28)
	v_pk_add_f32 v[72:73], v[72:73], v[216:217]
	v_pk_add_f32 v[74:75], v[74:75], v[218:219]
	global_store_dwordx4 v[160:161], v[72:75], off offset:128
	global_load_dwordx4 v[216:219], v[154:155], off offset:640
	s_waitcnt vmcnt(29)
	v_pk_add_f32 v[68:69], v[68:69], v[220:221]
	v_pk_add_f32 v[70:71], v[70:71], v[222:223]
	global_store_dwordx4 v[158:159], v[68:71], off offset:192
	global_load_dwordx4 v[220:223], v[152:153], off offset:704
	s_waitcnt vmcnt(30)
	v_pk_add_f32 v[64:65], v[64:65], v[224:225]
	v_pk_add_f32 v[66:67], v[66:67], v[226:227]
	global_store_dwordx4 v[160:161], v[64:67], off offset:192
	global_load_dwordx4 v[224:227], v[154:155], off offset:704
	s_waitcnt vmcnt(30)
	v_pk_add_f32 v[60:61], v[60:61], v[164:165]
	v_pk_add_f32 v[62:63], v[62:63], v[166:167]
	global_store_dwordx4 v[148:149], v[60:63], off offset:512
	s_waitcnt vmcnt(29)
	v_pk_add_f32 v[56:57], v[56:57], v[168:169]
	v_pk_add_f32 v[58:59], v[58:59], v[170:171]
	global_store_dwordx4 v[156:157], v[56:59], off offset:512
	s_waitcnt vmcnt(28)
	v_pk_add_f32 v[52:53], v[52:53], v[172:173]
	v_pk_add_f32 v[54:55], v[54:55], v[174:175]
	global_store_dwordx4 v[148:149], v[52:55], off offset:576
	s_waitcnt vmcnt(27)
	v_pk_add_f32 v[48:49], v[48:49], v[176:177]
	v_pk_add_f32 v[50:51], v[50:51], v[178:179]
	global_store_dwordx4 v[156:157], v[48:51], off offset:576
	s_waitcnt vmcnt(26)
	v_pk_add_f32 v[44:45], v[44:45], v[180:181]
	v_pk_add_f32 v[46:47], v[46:47], v[182:183]
	global_store_dwordx4 v[148:149], v[44:47], off offset:640
	s_waitcnt vmcnt(25)
	v_pk_add_f32 v[40:41], v[40:41], v[184:185]
	v_pk_add_f32 v[42:43], v[42:43], v[186:187]
	global_store_dwordx4 v[156:157], v[40:43], off offset:640
	s_waitcnt vmcnt(24)
	v_pk_add_f32 v[36:37], v[36:37], v[188:189]
	v_pk_add_f32 v[38:39], v[38:39], v[190:191]
	global_store_dwordx4 v[148:149], v[36:39], off offset:704
	s_waitcnt vmcnt(23)
	v_pk_add_f32 v[32:33], v[32:33], v[192:193]
	v_pk_add_f32 v[34:35], v[34:35], v[194:195]
	global_store_dwordx4 v[156:157], v[32:35], off offset:704
	s_waitcnt vmcnt(22)
	v_pk_add_f32 v[28:29], v[28:29], v[196:197]
	v_pk_add_f32 v[30:31], v[30:31], v[198:199]
	global_store_dwordx4 v[158:159], v[28:31], off offset:512
	s_waitcnt vmcnt(21)
	v_pk_add_f32 v[24:25], v[24:25], v[200:201]
	v_pk_add_f32 v[26:27], v[26:27], v[202:203]
	global_store_dwordx4 v[160:161], v[24:27], off offset:512
	s_waitcnt vmcnt(20)
	v_pk_add_f32 v[20:21], v[20:21], v[204:205]
	v_pk_add_f32 v[22:23], v[22:23], v[206:207]
	global_store_dwordx4 v[158:159], v[20:23], off offset:576
	s_waitcnt vmcnt(19)
	v_pk_add_f32 v[16:17], v[16:17], v[208:209]
	v_pk_add_f32 v[18:19], v[18:19], v[210:211]
	global_store_dwordx4 v[160:161], v[16:19], off offset:576
	s_waitcnt vmcnt(18)
	v_pk_add_f32 v[12:13], v[12:13], v[212:213]
	v_pk_add_f32 v[14:15], v[14:15], v[214:215]
	global_store_dwordx4 v[158:159], v[12:15], off offset:640
	s_waitcnt vmcnt(17)
	v_pk_add_f32 v[8:9], v[8:9], v[216:217]
	v_pk_add_f32 v[10:11], v[10:11], v[218:219]
	global_store_dwordx4 v[160:161], v[8:11], off offset:640
	s_waitcnt vmcnt(16)
	v_pk_add_f32 v[4:5], v[4:5], v[220:221]
	v_pk_add_f32 v[6:7], v[6:7], v[222:223]
	global_store_dwordx4 v[158:159], v[4:7], off offset:704
	s_waitcnt vmcnt(15)
	v_pk_add_f32 v[0:1], v[0:1], v[224:225]
	v_pk_add_f32 v[2:3], v[2:3], v[226:227]
	global_store_dwordx4 v[160:161], v[0:3], off offset:704
	s_cbranch_scc0 .LBB0_509

; __device__ __forceinline__ void gemm_tile(const TileDesc& td, char* shm_c, const int wv) {
;     ...
;   } else if (mode == EPI_RESID) {
;     #pragma unroll
;     for (int ai = 0; ai < 2; ++ai)
;     #pragma unroll
;     for (int bj = 0; bj < 2; ++bj)
;     #pragma unroll
;     for (int m = 0; m < 4; ++m)
;     #pragma unroll
;     for (int n = 0; n < 2; ++n) {
;       long o = (long)(td.bcol + bj * 128 + n * 16 + br_l) * D + (td.brow + ai * 128 + m * 16 + ar_l);
;       float4 r = *(const float4*)(td.aux + o);
;       f32x4 v = acc[ai][bj][m][n];
;       r.x += v[0]; r.y += v[1]; r.z += v[2]; r.w += v[3];
;       *(float4*)(td.outf + o) = r;
;     }
.LBB0_772:
	v_mbcnt_lo_u32_b32 v128, -1, 0
	v_mbcnt_hi_u32_b32 v128, -1, v128
	s_sext_i32_i16 s25, s25
	v_lshrrev_b32_e32 v130, 2, v128
	v_and_or_b32 v128, v128, 15, s42
	v_lshl_or_b32 v140, s25, 8, v128
	v_and_or_b32 v130, v130, 12, s38
	v_ashrrev_i32_e32 v141, 31, v140
	v_lshl_add_u32 v130, s24, 8, v130
	v_ashrrev_i32_e32 v131, 31, v130
	v_lshlrev_b64 v[132:133], 14, v[140:141]
	v_lshl_add_u64 v[132:133], s[70:71], 0, v[132:133]
	v_lshlrev_b64 v[148:149], 2, v[130:131]
	v_lshl_add_u64 v[132:133], v[132:133], 0, v[148:149]
	v_add_co_u32_e32 v134, vcc, 0x40000, v132
	s_nop 1
	v_addc_co_u32_e32 v135, vcc, 0, v133, vcc
	v_add_co_u32_e32 v136, vcc, 0x200000, v132
	s_nop 1
	v_addc_co_u32_e32 v137, vcc, 0, v133, vcc
	v_add_co_u32_e32 v138, vcc, 0x240000, v132
	s_nop 1
	v_addc_co_u32_e32 v139, vcc, 0, v133, vcc
	s_add_i32 s83, s83, s91
	s_cmpk_lt_i32 s83, 0x400
	global_load_dwordx4 v[144:147], v[132:133], off
	global_load_dwordx4 v[148:151], v[134:135], off
	global_load_dwordx4 v[152:155], v[132:133], off offset:64
	global_load_dwordx4 v[156:159], v[134:135], off offset:64
	global_load_dwordx4 v[160:163], v[132:133], off offset:128
	global_load_dwordx4 v[164:167], v[134:135], off offset:128
	global_load_dwordx4 v[168:171], v[132:133], off offset:192
	global_load_dwordx4 v[172:175], v[134:135], off offset:192
	global_load_dwordx4 v[176:179], v[136:137], off
	global_load_dwordx4 v[180:183], v[138:139], off
	global_load_dwordx4 v[184:187], v[136:137], off offset:64
	global_load_dwordx4 v[188:191], v[138:139], off offset:64
	global_load_dwordx4 v[192:195], v[136:137], off offset:128
	global_load_dwordx4 v[196:199], v[138:139], off offset:128
	global_load_dwordx4 v[200:203], v[136:137], off offset:192
	global_load_dwordx4 v[204:207], v[138:139], off offset:192
	s_waitcnt vmcnt(15)
	v_pk_add_f32 v[124:125], v[124:125], v[144:145]
	v_pk_add_f32 v[126:127], v[126:127], v[146:147]
	global_store_dwordx4 v[132:133], v[124:127], off
	global_load_dwordx4 v[144:147], v[132:133], off offset:512
	s_waitcnt vmcnt(16)
	v_pk_add_f32 v[120:121], v[120:121], v[148:149]
	v_pk_add_f32 v[122:123], v[122:123], v[150:151]
	global_store_dwordx4 v[134:135], v[120:123], off
	global_load_dwordx4 v[148:151], v[134:135], off offset:512
	s_waitcnt vmcnt(17)
	v_pk_add_f32 v[112:113], v[112:113], v[152:153]
	v_pk_add_f32 v[114:115], v[114:115], v[154:155]
	global_store_dwordx4 v[132:133], v[112:115], off offset:64
	global_load_dwordx4 v[152:155], v[132:133], off offset:576
	s_waitcnt vmcnt(18)
	v_pk_add_f32 v[116:117], v[116:117], v[156:157]
	v_pk_add_f32 v[118:119], v[118:119], v[158:159]
	global_store_dwordx4 v[134:135], v[116:119], off offset:64
	global_load_dwordx4 v[156:159], v[134:135], off offset:576
	s_waitcnt vmcnt(19)
	v_pk_add_f32 v[104:105], v[104:105], v[160:161]
	v_pk_add_f32 v[106:107], v[106:107], v[162:163]
	global_store_dwordx4 v[132:133], v[104:107], off offset:128
	global_load_dwordx4 v[160:163], v[132:133], off offset:640
	s_waitcnt vmcnt(20)
	v_pk_add_f32 v[108:109], v[108:109], v[164:165]
	v_pk_add_f32 v[110:111], v[110:111], v[166:167]
	global_store_dwordx4 v[134:135], v[108:111], off offset:128
	global_load_dwordx4 v[164:167], v[134:135], off offset:640
	s_waitcnt vmcnt(21)
	v_pk_add_f32 v[96:97], v[96:97], v[168:169]
	v_pk_add_f32 v[98:99], v[98:99], v[170:171]
	global_store_dwordx4 v[132:133], v[96:99], off offset:192
	global_load_dwordx4 v[168:171], v[132:133], off offset:704
	s_waitcnt vmcnt(22)
	v_pk_add_f32 v[100:101], v[100:101], v[172:173]
	v_pk_add_f32 v[102:103], v[102:103], v[174:175]
	global_store_dwordx4 v[134:135], v[100:103], off offset:192
	global_load_dwordx4 v[172:175], v[134:135], off offset:704
	s_waitcnt vmcnt(23)
	v_pk_add_f32 v[88:89], v[88:89], v[176:177]
	v_pk_add_f32 v[90:91], v[90:91], v[178:179]
	global_store_dwordx4 v[136:137], v[88:91], off
	global_load_dwordx4 v[176:179], v[136:137], off offset:512
	s_waitcnt vmcnt(24)
	v_pk_add_f32 v[92:93], v[92:93], v[180:181]
	v_pk_add_f32 v[94:95], v[94:95], v[182:183]
	global_store_dwordx4 v[138:139], v[92:95], off
	global_load_dwordx4 v[180:183], v[138:139], off offset:512
	s_waitcnt vmcnt(25)
; __device__ __forceinline__ void gemm_tile(const TileDesc& td, char* shm_c, const int wv) {
;     ...
;   } else if (mode == EPI_RESID) {
;     #pragma unroll
;     for (int ai = 0; ai < 2; ++ai)
;     #pragma unroll
;     for (int bj = 0; bj < 2; ++bj)
;     #pragma unroll
;     for (int m = 0; m < 4; ++m)
;     #pragma unroll
;     for (int n = 0; n < 2; ++n) {
;       long o = (long)(td.bcol + bj * 128 + n * 16 + br_l) * D + (td.brow + ai * 128 + m * 16 + ar_l);
;       float4 r = *(const float4*)(td.aux + o);
;       f32x4 v = acc[ai][bj][m][n];
;       r.x += v[0]; r.y += v[1]; r.z += v[2]; r.w += v[3];
;       *(float4*)(td.outf + o) = r;
;     }
	v_pk_add_f32 v[80:81], v[80:81], v[184:185]
	v_pk_add_f32 v[82:83], v[82:83], v[186:187]
	global_store_dwordx4 v[136:137], v[80:83], off offset:64
	global_load_dwordx4 v[184:187], v[136:137], off offset:576
	s_waitcnt vmcnt(26)
	v_pk_add_f32 v[84:85], v[84:85], v[188:189]
	v_pk_add_f32 v[86:87], v[86:87], v[190:191]
	global_store_dwordx4 v[138:139], v[84:87], off offset:64
	global_load_dwordx4 v[188:191], v[138:139], off offset:576
	s_waitcnt vmcnt(27)
	v_pk_add_f32 v[72:73], v[72:73], v[192:193]
	v_pk_add_f32 v[74:75], v[74:75], v[194:195]
	global_store_dwordx4 v[136:137], v[72:75], off offset:128
	global_load_dwordx4 v[192:195], v[136:137], off offset:640
	s_waitcnt vmcnt(28)
	v_pk_add_f32 v[76:77], v[76:77], v[196:197]
	v_pk_add_f32 v[78:79], v[78:79], v[198:199]
	global_store_dwordx4 v[138:139], v[76:79], off offset:128
	global_load_dwordx4 v[196:199], v[138:139], off offset:640
	s_waitcnt vmcnt(29)
	v_pk_add_f32 v[64:65], v[64:65], v[200:201]
	v_pk_add_f32 v[66:67], v[66:67], v[202:203]
	global_store_dwordx4 v[136:137], v[64:67], off offset:192
	global_load_dwordx4 v[200:203], v[136:137], off offset:704
	s_waitcnt vmcnt(30)
	v_pk_add_f32 v[68:69], v[68:69], v[204:205]
	v_pk_add_f32 v[70:71], v[70:71], v[206:207]
	global_store_dwordx4 v[138:139], v[68:71], off offset:192
	global_load_dwordx4 v[204:207], v[138:139], off offset:704
	s_waitcnt vmcnt(30)
	v_pk_add_f32 v[56:57], v[56:57], v[144:145]
	v_pk_add_f32 v[58:59], v[58:59], v[146:147]
	global_store_dwordx4 v[132:133], v[56:59], off offset:512
	s_waitcnt vmcnt(29)
	v_pk_add_f32 v[60:61], v[60:61], v[148:149]
	v_pk_add_f32 v[62:63], v[62:63], v[150:151]
	global_store_dwordx4 v[134:135], v[60:63], off offset:512
	s_waitcnt vmcnt(28)
	v_pk_add_f32 v[48:49], v[48:49], v[152:153]
	v_pk_add_f32 v[50:51], v[50:51], v[154:155]
	global_store_dwordx4 v[132:133], v[48:51], off offset:576
	s_waitcnt vmcnt(27)
	v_pk_add_f32 v[52:53], v[52:53], v[156:157]
	v_pk_add_f32 v[54:55], v[54:55], v[158:159]
	global_store_dwordx4 v[134:135], v[52:55], off offset:576
	s_waitcnt vmcnt(26)
	v_pk_add_f32 v[40:41], v[40:41], v[160:161]
	v_pk_add_f32 v[42:43], v[42:43], v[162:163]
	global_store_dwordx4 v[132:133], v[40:43], off offset:640
	s_waitcnt vmcnt(25)
	v_pk_add_f32 v[44:45], v[44:45], v[164:165]
	v_pk_add_f32 v[46:47], v[46:47], v[166:167]
	global_store_dwordx4 v[134:135], v[44:47], off offset:640
	s_waitcnt vmcnt(24)
	v_pk_add_f32 v[32:33], v[32:33], v[168:169]
	v_pk_add_f32 v[34:35], v[34:35], v[170:171]
	global_store_dwordx4 v[132:133], v[32:35], off offset:704
	s_waitcnt vmcnt(23)
	v_pk_add_f32 v[36:37], v[36:37], v[172:173]
	v_pk_add_f32 v[38:39], v[38:39], v[174:175]
	global_store_dwordx4 v[134:135], v[36:39], off offset:704
	s_waitcnt vmcnt(22)
	v_pk_add_f32 v[24:25], v[24:25], v[176:177]
	v_pk_add_f32 v[26:27], v[26:27], v[178:179]
	global_store_dwordx4 v[136:137], v[24:27], off offset:512
	s_waitcnt vmcnt(21)
	v_pk_add_f32 v[28:29], v[28:29], v[180:181]
	v_pk_add_f32 v[30:31], v[30:31], v[182:183]
	global_store_dwordx4 v[138:139], v[28:31], off offset:512
	s_waitcnt vmcnt(20)
	v_pk_add_f32 v[16:17], v[16:17], v[184:185]
	v_pk_add_f32 v[18:19], v[18:19], v[186:187]
	global_store_dwordx4 v[136:137], v[16:19], off offset:576
	s_waitcnt vmcnt(19)
	v_pk_add_f32 v[20:21], v[20:21], v[188:189]
	v_pk_add_f32 v[22:23], v[22:23], v[190:191]
	global_store_dwordx4 v[138:139], v[20:23], off offset:576
	s_waitcnt vmcnt(18)
	v_pk_add_f32 v[8:9], v[8:9], v[192:193]
	v_pk_add_f32 v[10:11], v[10:11], v[194:195]
	global_store_dwordx4 v[136:137], v[8:11], off offset:640
	s_waitcnt vmcnt(17)
	v_pk_add_f32 v[12:13], v[12:13], v[196:197]
	v_pk_add_f32 v[14:15], v[14:15], v[198:199]
	global_store_dwordx4 v[138:139], v[12:15], off offset:640
	s_waitcnt vmcnt(16)
	v_pk_add_f32 v[0:1], v[0:1], v[200:201]
	v_pk_add_f32 v[2:3], v[2:3], v[202:203]
	global_store_dwordx4 v[136:137], v[0:3], off offset:704
	s_waitcnt vmcnt(15)
	v_pk_add_f32 v[4:5], v[4:5], v[204:205]
	v_pk_add_f32 v[6:7], v[6:7], v[206:207]
	global_store_dwordx4 v[138:139], v[4:7], off offset:704
	s_cbranch_scc0 .LBB0_783
